# staging writes before MFMA slot 19 of 20 (two MFMAs of cover)
# speedup vs baseline: 1.0014x; 1.0014x over previous
.LBB0_548:
	s_cmp_gt_u32 s52, s51
	s_mul_i32 s61, s25, 0x2200
	s_cbranch_scc1 .LBB0_550
	s_and_b32 s42, s52, 2
	s_mulk_i32 s42, 0x3400
	v_add_u32_e32 v0, s42, v160
	v_add_u32_e32 v242, s61, v161
	v_add_u32_e32 v163, 0xe000, v242
	v_add_u32_e32 v242, 0xd000, v242
	ds_read_b128 v[82:85], v0 offset:13312
	ds_read_b128 v[98:101], v0 offset:19968
	ds_read_b128 v[164:167], v0 offset:13344
	ds_read_b128 v[168:171], v0 offset:20000
	ds_read2_b64 v[238:241], v242 offset0:0 offset1:2
	ds_read2_b64 v[234:237], v163 offset0:32 offset1:34
	ds_read_b128 v[172:175], v0 offset:13376
	ds_read_b128 v[176:179], v0 offset:20032
	ds_read_b128 v[180:183], v0 offset:13408
	ds_read_b128 v[184:187], v0 offset:20064
	ds_read_b128 v[188:191], v0 offset:13440
	ds_read_b128 v[192:195], v0 offset:20096
	ds_read_b128 v[196:199], v0 offset:13472
	ds_read_b128 v[220:223], v0 offset:20128
	v_exp_f32_e32 v50, v50
	v_exp_f32_e32 v51, v51
	v_exp_f32_e32 v52, v52
	v_exp_f32_e32 v53, v53
	v_exp_f32_e32 v54, v54
	v_exp_f32_e32 v55, v55
	v_exp_f32_e32 v56, v56
	v_exp_f32_e32 v57, v57
	s_waitcnt lgkmcnt(13)
	v_mfma_f32_32x32x16_bf16 v[82:97], v[82:85], v[122:125], 0
	v_cvt_pk_bf16_f32 v224, v50, v51
	v_cvt_pk_bf16_f32 v225, v52, v53
	v_cvt_pk_bf16_f32 v226, v54, v55
	v_cvt_pk_bf16_f32 v227, v56, v57
	v_exp_f32_e32 v58, v58
	v_add_f32_e32 v200, v50, v51
	s_waitcnt lgkmcnt(12)
	v_mfma_f32_32x32x16_bf16 v[98:113], v[98:101], v[122:125], 0
	v_exp_f32_e32 v59, v59
	v_exp_f32_e32 v60, v60
	v_add_f32_e32 v201, v52, v53
	v_exp_f32_e32 v61, v61
	s_waitcnt lgkmcnt(11)
	v_mfma_f32_32x32x16_bf16 v[82:97], v[164:167], v[126:129], v[82:97]
	v_exp_f32_e32 v62, v62
	v_add_f32_e32 v200, v200, v54
	v_exp_f32_e32 v63, v63
	v_add_f32_e32 v201, v201, v55
	v_exp_f32_e32 v64, v64
	s_waitcnt lgkmcnt(10)
	v_mfma_f32_32x32x16_bf16 v[98:113], v[168:171], v[126:129], v[98:113]
	ds_read2_b64 v[164:167], v242 offset0:4 offset1:6
	ds_read2_b64 v[168:171], v163 offset0:36 offset1:38
	v_add_f32_e32 v200, v200, v56
	v_exp_f32_e32 v65, v65
	v_add_f32_e32 v201, v201, v57
	v_cvt_pk_bf16_f32 v228, v58, v59
	v_cvt_pk_bf16_f32 v229, v60, v61
	s_waitcnt lgkmcnt(11)
	v_mfma_f32_32x32x16_bf16 v[18:33], v[238:241], v[224:227], v[18:33]
	v_cvt_pk_bf16_f32 v230, v62, v63
	v_cvt_pk_bf16_f32 v231, v64, v65
	v_exp_f32_e32 v66, v66
	v_add_f32_e32 v200, v200, v58
	v_exp_f32_e32 v67, v67
	v_add_f32_e32 v201, v201, v59
	s_waitcnt lgkmcnt(10)
	v_mfma_f32_32x32x16_bf16 v[34:49], v[234:237], v[224:227], v[34:49]
	v_exp_f32_e32 v68, v68
	v_add_f32_e32 v200, v200, v60
	v_exp_f32_e32 v69, v69
	v_add_f32_e32 v201, v201, v61
	v_exp_f32_e32 v70, v70
	s_waitcnt lgkmcnt(9)
	v_mfma_f32_32x32x16_bf16 v[82:97], v[172:175], v[134:137], v[82:97]
	v_add_f32_e32 v200, v200, v62
	v_exp_f32_e32 v71, v71
	v_add_f32_e32 v201, v201, v63
	v_exp_f32_e32 v72, v72
	v_add_f32_e32 v200, v200, v64
	s_waitcnt lgkmcnt(8)
	v_mfma_f32_32x32x16_bf16 v[98:113], v[176:179], v[134:137], v[98:113]
	ds_read2_b64 v[172:175], v242 offset0:8 offset1:10
	ds_read2_b64 v[176:179], v163 offset0:40 offset1:42
	v_exp_f32_e32 v73, v73
	v_add_f32_e32 v201, v201, v65
	v_cvt_pk_bf16_f32 v224, v66, v67
	v_cvt_pk_bf16_f32 v225, v68, v69
	v_cvt_pk_bf16_f32 v226, v70, v71
	s_waitcnt lgkmcnt(3)
	v_mfma_f32_32x32x16_bf16 v[18:33], v[164:167], v[228:231], v[18:33]
	v_cvt_pk_bf16_f32 v227, v72, v73
	v_exp_f32_e32 v74, v74
	v_add_f32_e32 v200, v200, v66
	v_exp_f32_e32 v75, v75
	v_add_f32_e32 v201, v201, v67
	s_waitcnt lgkmcnt(2)
	v_mfma_f32_32x32x16_bf16 v[34:49], v[168:171], v[228:231], v[34:49]
	v_exp_f32_e32 v76, v76
	v_add_f32_e32 v200, v200, v68
	v_exp_f32_e32 v77, v77
	v_add_f32_e32 v201, v201, v69
	v_exp_f32_e32 v78, v78
	s_waitcnt lgkmcnt(9)
	v_mfma_f32_32x32x16_bf16 v[82:97], v[180:183], v[138:141], v[82:97]
	v_add_f32_e32 v200, v200, v70
	v_exp_f32_e32 v79, v79
	v_add_f32_e32 v201, v201, v71
	v_exp_f32_e32 v80, v80
	v_add_f32_e32 v200, v200, v72
	s_waitcnt lgkmcnt(8)
	v_mfma_f32_32x32x16_bf16 v[98:113], v[184:187], v[138:141], v[98:113]
	ds_read2_b64 v[180:183], v242 offset0:12 offset1:14
	ds_read2_b64 v[184:187], v163 offset0:44 offset1:46
	v_exp_f32_e32 v81, v81
	v_add_f32_e32 v201, v201, v73
	v_cvt_pk_bf16_f32 v228, v74, v75
	v_cvt_pk_bf16_f32 v229, v76, v77
	v_cvt_pk_bf16_f32 v230, v78, v79
	s_waitcnt lgkmcnt(3)
	v_mfma_f32_32x32x16_bf16 v[18:33], v[172:175], v[224:227], v[18:33]
	v_cvt_pk_bf16_f32 v231, v80, v81
	v_add_f32_e32 v200, v200, v74
	v_add_f32_e32 v201, v201, v75
	v_add_f32_e32 v200, v200, v76
	v_add_f32_e32 v201, v201, v77
	v_add_f32_e32 v200, v200, v78
	v_add_f32_e32 v201, v201, v79
	v_add_f32_e32 v200, v200, v80
	s_waitcnt lgkmcnt(2)
	v_mfma_f32_32x32x16_bf16 v[34:49], v[176:179], v[224:227], v[34:49]
	v_add_f32_e32 v201, v201, v81
	v_add_f32_e32 v200, v200, v201
	v_add_f32_e32 v162, v162, v200
	s_waitcnt lgkmcnt(9)
	v_mfma_f32_32x32x16_bf16 v[82:97], v[188:191], v[142:145], v[82:97]
	s_waitcnt lgkmcnt(8)
	v_mfma_f32_32x32x16_bf16 v[98:113], v[192:195], v[142:145], v[98:113]
	s_waitcnt lgkmcnt(7)
	v_mfma_f32_32x32x16_bf16 v[82:97], v[196:199], v[146:149], v[82:97]
	s_waitcnt lgkmcnt(6)
	v_mfma_f32_32x32x16_bf16 v[98:113], v[220:223], v[146:149], v[98:113]
	s_waitcnt lgkmcnt(0)
	v_cndmask_b32_e64 v0, 0, 1, s[44:45]
	v_cmp_ne_u32_e64 s[42:43], 1, v0
	s_andn2_b64 vcc, exec, s[44:45]
	s_cbranch_vccnz .Lt1a_mid
	s_and_b32 s44, s53, 2
	s_mulk_i32 s44, 0x3400
	s_add_i32 s62, s44, 0
	v_add_u32_e32 v0, s62, v151
	s_waitcnt vmcnt(0)
	ds_write_b128 v0, v[118:121]
	s_and_saveexec_b64 s[44:45], s[40:41]
	v_add_u32_e32 v0, s62, v159
	ds_write_b128 v0, v[6:9]
	s_or_b64 exec, exec, s[44:45]

.Lt1a_end:
	v_mfma_f32_32x32x16_bf16 v[18:33], v[180:183], v[228:231], v[18:33]
	v_mfma_f32_32x32x16_bf16 v[34:49], v[184:187], v[228:231], v[34:49]
	s_branch .LBB0_556

.LBB0_563:
	s_cmp_ge_u32 s52, s51
	s_mul_i32 s58, s25, 0x2200
	s_cbranch_scc1 .LBB0_565
	s_andn2_b32 s52, 2, s52
	s_mulk_i32 s52, 0x3400
	v_add_u32_e32 v0, s52, v160
	v_add_u32_e32 v242, s58, v161
	v_add_u32_e32 v163, 0xe000, v242
	v_add_u32_e32 v242, 0xd000, v242
	ds_read_b128 v[50:53], v0 offset:0
	ds_read_b128 v[66:69], v0 offset:6656
	ds_read_b128 v[164:167], v0 offset:32
	ds_read_b128 v[168:171], v0 offset:6688
	ds_read2_b64 v[238:241], v242 offset0:0 offset1:2
	ds_read2_b64 v[234:237], v163 offset0:32 offset1:34
	ds_read_b128 v[172:175], v0 offset:64
	ds_read_b128 v[176:179], v0 offset:6720
	ds_read_b128 v[180:183], v0 offset:96
	ds_read_b128 v[184:187], v0 offset:6752
	ds_read_b128 v[188:191], v0 offset:128
	ds_read_b128 v[192:195], v0 offset:6784
	ds_read_b128 v[196:199], v0 offset:160
	ds_read_b128 v[220:223], v0 offset:6816
	v_exp_f32_e32 v82, v82
	v_exp_f32_e32 v83, v83
	v_exp_f32_e32 v84, v84
	v_exp_f32_e32 v85, v85
	v_exp_f32_e32 v86, v86
	v_exp_f32_e32 v87, v87
	v_exp_f32_e32 v88, v88
	v_exp_f32_e32 v89, v89
	s_waitcnt lgkmcnt(13)
	v_mfma_f32_32x32x16_bf16 v[50:65], v[50:53], v[122:125], 0
	v_cvt_pk_bf16_f32 v224, v82, v83
	v_cvt_pk_bf16_f32 v225, v84, v85
	v_cvt_pk_bf16_f32 v226, v86, v87
	v_cvt_pk_bf16_f32 v227, v88, v89
	v_exp_f32_e32 v90, v90
	v_add_f32_e32 v200, v82, v83
	s_waitcnt lgkmcnt(12)
	v_mfma_f32_32x32x16_bf16 v[66:81], v[66:69], v[122:125], 0
	v_exp_f32_e32 v91, v91
	v_exp_f32_e32 v92, v92
	v_add_f32_e32 v201, v84, v85
	v_exp_f32_e32 v93, v93
	s_waitcnt lgkmcnt(11)
	v_mfma_f32_32x32x16_bf16 v[50:65], v[164:167], v[126:129], v[50:65]
	v_exp_f32_e32 v94, v94
	v_add_f32_e32 v200, v200, v86
	v_exp_f32_e32 v95, v95
	v_add_f32_e32 v201, v201, v87
	v_exp_f32_e32 v96, v96
	s_waitcnt lgkmcnt(10)
	v_mfma_f32_32x32x16_bf16 v[66:81], v[168:171], v[126:129], v[66:81]
	ds_read2_b64 v[164:167], v242 offset0:4 offset1:6
	ds_read2_b64 v[168:171], v163 offset0:36 offset1:38
	v_add_f32_e32 v200, v200, v88
	v_exp_f32_e32 v97, v97
	v_add_f32_e32 v201, v201, v89
	v_cvt_pk_bf16_f32 v228, v90, v91
	v_cvt_pk_bf16_f32 v229, v92, v93
	s_waitcnt lgkmcnt(11)
	v_mfma_f32_32x32x16_bf16 v[18:33], v[238:241], v[224:227], v[18:33]
	v_cvt_pk_bf16_f32 v230, v94, v95
	v_cvt_pk_bf16_f32 v231, v96, v97
	v_exp_f32_e32 v98, v98
	v_add_f32_e32 v200, v200, v90
	v_exp_f32_e32 v99, v99
	v_add_f32_e32 v201, v201, v91
	s_waitcnt lgkmcnt(10)
	v_mfma_f32_32x32x16_bf16 v[34:49], v[234:237], v[224:227], v[34:49]
	v_exp_f32_e32 v100, v100
	v_add_f32_e32 v200, v200, v92
	v_exp_f32_e32 v101, v101
	v_add_f32_e32 v201, v201, v93
	v_exp_f32_e32 v102, v102
	s_waitcnt lgkmcnt(9)
	v_mfma_f32_32x32x16_bf16 v[50:65], v[172:175], v[134:137], v[50:65]
	v_add_f32_e32 v200, v200, v94
	v_exp_f32_e32 v103, v103
	v_add_f32_e32 v201, v201, v95
	v_exp_f32_e32 v104, v104
	v_add_f32_e32 v200, v200, v96
	s_waitcnt lgkmcnt(8)
	v_mfma_f32_32x32x16_bf16 v[66:81], v[176:179], v[134:137], v[66:81]
	ds_read2_b64 v[172:175], v242 offset0:8 offset1:10
	ds_read2_b64 v[176:179], v163 offset0:40 offset1:42
	v_exp_f32_e32 v105, v105
	v_add_f32_e32 v201, v201, v97
	v_cvt_pk_bf16_f32 v224, v98, v99
	v_cvt_pk_bf16_f32 v225, v100, v101
	v_cvt_pk_bf16_f32 v226, v102, v103
	s_waitcnt lgkmcnt(3)
	v_mfma_f32_32x32x16_bf16 v[18:33], v[164:167], v[228:231], v[18:33]
	v_cvt_pk_bf16_f32 v227, v104, v105
	v_exp_f32_e32 v106, v106
	v_add_f32_e32 v200, v200, v98
	v_exp_f32_e32 v107, v107
	v_add_f32_e32 v201, v201, v99
	s_waitcnt lgkmcnt(2)
	v_mfma_f32_32x32x16_bf16 v[34:49], v[168:171], v[228:231], v[34:49]
	v_exp_f32_e32 v108, v108
	v_add_f32_e32 v200, v200, v100
	v_exp_f32_e32 v109, v109
	v_add_f32_e32 v201, v201, v101
	v_exp_f32_e32 v110, v110
	s_waitcnt lgkmcnt(9)
	v_mfma_f32_32x32x16_bf16 v[50:65], v[180:183], v[138:141], v[50:65]
	v_add_f32_e32 v200, v200, v102
	v_exp_f32_e32 v111, v111
	v_add_f32_e32 v201, v201, v103
	v_exp_f32_e32 v112, v112
	v_add_f32_e32 v200, v200, v104
	s_waitcnt lgkmcnt(8)
	v_mfma_f32_32x32x16_bf16 v[66:81], v[184:187], v[138:141], v[66:81]
	ds_read2_b64 v[180:183], v242 offset0:12 offset1:14
	ds_read2_b64 v[184:187], v163 offset0:44 offset1:46
	v_exp_f32_e32 v113, v113
	v_add_f32_e32 v201, v201, v105
	v_cvt_pk_bf16_f32 v228, v106, v107
	v_cvt_pk_bf16_f32 v229, v108, v109
	v_cvt_pk_bf16_f32 v230, v110, v111
	s_waitcnt lgkmcnt(3)
	v_mfma_f32_32x32x16_bf16 v[18:33], v[172:175], v[224:227], v[18:33]
	v_cvt_pk_bf16_f32 v231, v112, v113
	v_add_f32_e32 v200, v200, v106
	v_add_f32_e32 v201, v201, v107
	v_add_f32_e32 v200, v200, v108
	v_add_f32_e32 v201, v201, v109
	v_add_f32_e32 v200, v200, v110
	v_add_f32_e32 v201, v201, v111
	v_add_f32_e32 v200, v200, v112
	s_waitcnt lgkmcnt(2)
	v_mfma_f32_32x32x16_bf16 v[34:49], v[176:179], v[224:227], v[34:49]
	v_add_f32_e32 v201, v201, v113
	v_add_f32_e32 v200, v200, v201
	v_add_f32_e32 v162, v162, v200
	s_waitcnt lgkmcnt(9)
	v_mfma_f32_32x32x16_bf16 v[50:65], v[188:191], v[142:145], v[50:65]
	s_waitcnt lgkmcnt(8)
	v_mfma_f32_32x32x16_bf16 v[66:81], v[192:195], v[142:145], v[66:81]
	s_waitcnt lgkmcnt(7)
	v_mfma_f32_32x32x16_bf16 v[50:65], v[196:199], v[146:149], v[50:65]
	s_waitcnt lgkmcnt(6)
	v_mfma_f32_32x32x16_bf16 v[66:81], v[220:223], v[146:149], v[66:81]
	s_waitcnt lgkmcnt(0)
	s_and_b64 vcc, exec, s[44:45]
	s_cbranch_vccnz .Lt2a_mid
	s_and_b32 s44, s60, 3
	s_mulk_i32 s44, 0x3400
	s_add_i32 s52, s44, 0
	v_add_u32_e32 v0, s52, v151
	s_waitcnt vmcnt(0)
	ds_write_b128 v0, v[2:5]
	s_and_saveexec_b64 s[44:45], s[40:41]
	v_add_u32_e32 v0, s52, v159
	ds_write_b128 v0, v[10:13]
	s_or_b64 exec, exec, s[44:45]
